# P1: wave sums via DPP row_shr/row_bcast instead of 54 ds_bpermute round trips per row (f32)
# speedup vs baseline: 1.0226x; 1.0052x over previous
; __device__ __forceinline__ unsigned pk2(float lo, float hi) { unsigned r; asm("v_cvt_pk_bf16_f32 %0, %1, %2" : "=v"(r) : "v"(lo), "v"(hi)); return r; }
; __device__ __forceinline__ void phase1(const Args& a, LAS unsigned char* L) {
;     ...
;         for (int j = 0; j < 4; ++j) ss += (v[j][0] * v[j][0] + v[j][1] * v[j][1]) + (v[j][2] * v[j][2] + v[j][3] * v[j][3]);
;         const float rr = rsqrtf(wave_sum(ss) * (1.f / DM) + EPS);
;         float gacc[8];
; #pragma unroll
;         for (int q = 0; q < 8; ++q) gacc[q] = 0.f;
; #pragma unroll
;         for (int j = 0; j < 4; ++j) { const f32x4 h = v[j] * rr * gsv[j] + shv[j];
;             *(u32x2*)(HB + (size_t)m * DM + 4 * lane + 256 * j) = (u32x2){pk2(h[0], h[1]), pk2(h[2], h[3])};
; #pragma unroll
;             for (int i = 0; i < 4; ++i) { const f32x4 w0 = wg[((j * 4 + i) * 2) * 64 + lane], w1 = wg[((j * 4 + i) * 2 + 1) * 64 + lane];
;                 gacc[0] += h[i] * w0[0]; gacc[1] += h[i] * w0[1]; gacc[2] += h[i] * w0[2]; gacc[3] += h[i] * w0[3];
;                 gacc[4] += h[i] * w1[0]; gacc[5] += h[i] * w1[1]; gacc[6] += h[i] * w1[2]; gacc[7] += h[i] * w1[3]; } }
.LBB0_121:
	v_pk_mul_f32 v[2:3], v[34:35], v[34:35]
	v_pk_mul_f32 v[84:85], v[32:33], v[32:33]
	v_mov_b32_e32 v87, v3
	v_mov_b32_e32 v86, v84
	v_pk_mov_b32 v[2:3], v[84:85], v[2:3] op_sel:[1,0]
	v_pk_mul_f32 v[84:85], v[30:31], v[30:31]
	v_pk_add_f32 v[2:3], v[2:3], v[86:87]
	v_pk_mul_f32 v[86:87], v[28:29], v[28:29]
	v_mov_b32_e32 v89, v85
	v_mov_b32_e32 v88, v86
	v_pk_mov_b32 v[84:85], v[86:87], v[84:85] op_sel:[1,0]
	v_mul_f32_e32 v0, v24, v24
	v_pk_add_f32 v[84:85], v[84:85], v[88:89]
	v_pk_fma_f32 v[86:87], v[24:25], v[24:25], v[0:1] op_sel_hi:[1,1,0]
	v_mul_f32_e32 v0, v26, v26
	v_pk_add_f32 v[2:3], v[2:3], v[2:3] op_sel_hi:[0,1]
	v_pk_add_f32 v[84:85], v[84:85], v[84:85] op_sel_hi:[0,1]
	v_pk_fma_f32 v[88:89], v[26:27], v[26:27], v[0:1] op_sel_hi:[1,1,0]
	v_mul_f32_e32 v86, v20, v20
	v_mul_f32_e32 v88, v21, v21
	v_mul_f32_e32 v84, v22, v22
	v_mul_f32_e32 v2, v23, v23
	v_pk_add_f32 v[86:87], v[86:87], v[88:89]
	v_pk_add_f32 v[2:3], v[84:85], v[2:3]
	s_nop 0
	v_pk_add_f32 v[2:3], v[86:87], v[2:3]
	ds_read_b128 v[84:87], v187
	ds_read_b128 v[88:91], v187 offset:1024
	ds_read_b128 v[92:95], v187 offset:2048
	ds_read_b128 v[96:99], v187 offset:3072
	v_add_f32_e32 v0, v2, v3
	s_nop 1
	v_add_f32_dpp v0, v0, v0 row_shr:1 row_mask:0xf bank_mask:0xf bound_ctrl:1
	s_nop 1
	v_add_f32_dpp v0, v0, v0 row_shr:2 row_mask:0xf bank_mask:0xf bound_ctrl:1
	s_nop 1
	v_add_f32_dpp v0, v0, v0 row_shr:4 row_mask:0xf bank_mask:0xf bound_ctrl:1
	s_nop 1
	v_add_f32_dpp v0, v0, v0 row_shr:8 row_mask:0xf bank_mask:0xf bound_ctrl:1
	s_nop 1
	v_add_f32_dpp v0, v0, v0 row_bcast:15 row_mask:0xa bank_mask:0xf
	s_nop 1
	v_add_f32_dpp v0, v0, v0 row_bcast:31 row_mask:0xc bank_mask:0xf
	s_nop 0
	v_readlane_b32 s0, v0, 63
	s_waitcnt lgkmcnt(0)
	s_nop 0
	v_mov_b32_e32 v0, s0
	v_fmamk_f32 v0, v0, 0x3a800000, v191
	v_mul_f32_e32 v2, 0x4b800000, v0
	v_cmp_gt_f32_e64 s[0:1], s5, v0
	s_nop 1
	v_cndmask_b32_e64 v0, v0, v2, s[0:1]
	v_rsq_f32_e32 v0, v0
	s_nop 0
	v_mul_f32_e32 v2, 0x45800000, v0
	v_cndmask_b32_e64 v0, v0, v2, s[0:1]
	v_pk_mul_f32 v[2:3], v[32:33], v[0:1] op_sel_hi:[1,0]
	v_pk_mul_f32 v[32:33], v[34:35], v[0:1] op_sel_hi:[1,0]
	v_pk_fma_f32 v[134:135], v[40:41], v[2:3], v[36:37]
	v_pk_fma_f32 v[132:133], v[42:43], v[32:33], v[38:39]
	v_cvt_pk_bf16_f32 v2, v134, v135
	v_pk_fma_f32 v[142:143], v[84:85], v[134:135], 0 op_sel_hi:[1,0,0]
	v_cvt_pk_bf16_f32 v3, v132, v133
	global_store_dwordx2 v[178:179], v[2:3], off
	ds_read_b128 v[32:35], v187 offset:4096
	ds_read_b128 v[100:103], v187 offset:5120
	ds_read_b128 v[104:107], v187 offset:6144
	ds_read_b128 v[108:111], v187 offset:7168
	v_pk_mul_f32 v[2:3], v[28:29], v[0:1] op_sel_hi:[1,0]
	v_pk_mul_f32 v[28:29], v[30:31], v[0:1] op_sel_hi:[1,0]
	v_pk_fma_f32 v[144:145], v[86:87], v[134:135], 0 op_sel_hi:[1,0,0]
	v_pk_fma_f32 v[92:93], v[92:93], v[134:135], v[142:143] op_sel:[0,1,0]
	v_pk_fma_f32 v[136:137], v[50:51], v[28:29], v[46:47]
	v_pk_fma_f32 v[138:139], v[48:49], v[2:3], v[44:45]
	v_cvt_pk_bf16_f32 v3, v136, v137
	v_pk_fma_f32 v[94:95], v[94:95], v[134:135], v[144:145] op_sel:[0,1,0]
	v_cvt_pk_bf16_f32 v2, v138, v139
	global_store_dwordx2 v[178:179], v[2:3], off offset:512
	s_waitcnt lgkmcnt(3)
	v_pk_fma_f32 v[32:33], v[32:33], v[132:133], v[92:93] op_sel_hi:[1,0,1]
	ds_read_b128 v[28:31], v187 offset:8192
	ds_read_b128 v[112:115], v187 offset:9216
	ds_read_b128 v[116:119], v187 offset:10240
	ds_read_b128 v[120:123], v187 offset:11264
	ds_read_b128 v[124:127], v187 offset:12288
	ds_read_b128 v[128:131], v187 offset:13312
	s_waitcnt lgkmcnt(7)
	v_pk_fma_f32 v[104:105], v[104:105], v[132:133], v[32:33] op_sel:[0,1,0]
	v_pk_fma_f32 v[32:33], v[34:35], v[132:133], v[94:95] op_sel_hi:[1,0,1]
	s_waitcnt lgkmcnt(5)
	v_pk_fma_f32 v[28:29], v[138:139], v[28:29], v[104:105] op_sel_hi:[0,1,1]
	v_pk_fma_f32 v[106:107], v[106:107], v[132:133], v[32:33] op_sel:[0,1,0]
	v_pk_mul_f32 v[2:3], v[24:25], v[0:1] op_sel_hi:[1,0]
	v_pk_mul_f32 v[140:141], v[26:27], v[0:1] op_sel_hi:[1,0]
	ds_read_b128 v[24:27], v187 offset:14336
	ds_read_b128 v[84:87], v187 offset:15360
	s_waitcnt lgkmcnt(5)
	v_pk_fma_f32 v[116:117], v[138:139], v[116:117], v[28:29] op_sel:[1,0,0]
	v_pk_fma_f32 v[28:29], v[138:139], v[30:31], v[106:107] op_sel_hi:[0,1,1]
	ds_read_b128 v[32:35], v187 offset:16384
	ds_read_b128 v[92:95], v187 offset:17408
	v_pk_fma_f32 v[118:119], v[138:139], v[118:119], v[28:29] op_sel:[1,0,0]
	ds_read_b128 v[28:31], v187 offset:18432
	ds_read_b128 v[104:107], v187 offset:19456
	s_waitcnt lgkmcnt(7)
	v_pk_fma_f32 v[124:125], v[136:137], v[124:125], v[116:117] op_sel_hi:[0,1,1]
	v_pk_fma_f32 v[126:127], v[136:137], v[126:127], v[118:119] op_sel_hi:[0,1,1]
	ds_read_b128 v[116:119], v187 offset:20480
	v_pk_fma_f32 v[146:147], v[56:57], v[2:3], v[52:53]
	s_waitcnt lgkmcnt(6)
	v_pk_fma_f32 v[124:125], v[136:137], v[24:25], v[124:125] op_sel:[1,0,0]
	v_pk_fma_f32 v[140:141], v[58:59], v[140:141], v[54:55]
	s_waitcnt lgkmcnt(4)
	v_pk_fma_f32 v[32:33], v[146:147], v[32:33], v[124:125] op_sel_hi:[0,1,1]
	v_pk_fma_f32 v[126:127], v[136:137], v[26:27], v[126:127] op_sel:[1,0,0]
	s_waitcnt lgkmcnt(2)
	v_pk_fma_f32 v[28:29], v[146:147], v[28:29], v[32:33] op_sel:[1,0,0]
	ds_read_b128 v[24:27], v187 offset:21504
	s_waitcnt lgkmcnt(1)
; __device__ __forceinline__ unsigned pk2(float lo, float hi) { unsigned r; asm("v_cvt_pk_bf16_f32 %0, %1, %2" : "=v"(r) : "v"(lo), "v"(hi)); return r; }
; __device__ __forceinline__ void phase1(const Args& a, LAS unsigned char* L) {
;     ...
;         for (int j = 0; j < 4; ++j) { const f32x4 h = v[j] * rr * gsv[j] + shv[j];
;             *(u32x2*)(HB + (size_t)m * DM + 4 * lane + 256 * j) = (u32x2){pk2(h[0], h[1]), pk2(h[2], h[3])};
; #pragma unroll
;             for (int i = 0; i < 4; ++i) { const f32x4 w0 = wg[((j * 4 + i) * 2) * 64 + lane], w1 = wg[((j * 4 + i) * 2 + 1) * 64 + lane];
;                 gacc[0] += h[i] * w0[0]; gacc[1] += h[i] * w0[1]; gacc[2] += h[i] * w0[2]; gacc[3] += h[i] * w0[3];
;                 gacc[4] += h[i] * w1[0]; gacc[5] += h[i] * w1[1]; gacc[6] += h[i] * w1[2]; gacc[7] += h[i] * w1[3]; } }
; #pragma unroll
;         for (int q = 0; q < 8; ++q) gacc[q] = wave_sum(gacc[q]);
	v_pk_fma_f32 v[124:125], v[140:141], v[116:117], v[28:29] op_sel_hi:[0,1,1]
	v_pk_fma_f32 v[28:29], v[146:147], v[34:35], v[126:127] op_sel_hi:[0,1,1]
	v_pk_fma_f32 v[28:29], v[146:147], v[30:31], v[28:29] op_sel:[1,0,0]
	v_pk_mul_f32 v[20:21], v[20:21], v[0:1] op_sel_hi:[1,0]
	v_pk_fma_f32 v[126:127], v[140:141], v[118:119], v[28:29] op_sel_hi:[0,1,1]
	v_pk_fma_f32 v[28:29], v[88:89], v[134:135], 0 op_sel_hi:[1,0,0]
	v_pk_mul_f32 v[22:23], v[22:23], v[0:1] op_sel_hi:[1,0]
	v_pk_fma_f32 v[28:29], v[96:97], v[134:135], v[28:29] op_sel:[0,1,0]
	v_cvt_pk_bf16_f32 v2, v146, v147
	v_cvt_pk_bf16_f32 v3, v140, v141
	s_nop 0
	v_pk_fma_f32 v[28:29], v[100:101], v[132:133], v[28:29] op_sel_hi:[1,0,1]
	s_nop 0
	v_pk_fma_f32 v[28:29], v[108:109], v[132:133], v[28:29] op_sel:[0,1,0]
	s_nop 0
	v_pk_fma_f32 v[28:29], v[138:139], v[112:113], v[28:29] op_sel_hi:[0,1,1]
	v_pk_fma_f32 v[28:29], v[138:139], v[120:121], v[28:29] op_sel:[1,0,0]
	s_nop 0
	v_pk_fma_f32 v[28:29], v[136:137], v[128:129], v[28:29] op_sel_hi:[0,1,1]
	v_pk_fma_f32 v[84:85], v[136:137], v[84:85], v[28:29] op_sel:[1,0,0]
	v_pk_fma_f32 v[28:29], v[90:91], v[134:135], 0 op_sel_hi:[1,0,0]
	v_pk_fma_f32 v[84:85], v[146:147], v[92:93], v[84:85] op_sel_hi:[0,1,1]
	v_pk_fma_f32 v[28:29], v[98:99], v[134:135], v[28:29] op_sel:[0,1,0]
	v_pk_fma_f32 v[134:135], v[64:65], v[20:21], v[60:61]
	v_pk_fma_f32 v[28:29], v[102:103], v[132:133], v[28:29] op_sel_hi:[1,0,1]
	v_pk_fma_f32 v[84:85], v[146:147], v[104:105], v[84:85] op_sel:[1,0,0]
	v_pk_fma_f32 v[28:29], v[110:111], v[132:133], v[28:29] op_sel:[0,1,0]
	v_pk_fma_f32 v[132:133], v[66:67], v[22:23], v[62:63]
	v_pk_fma_f32 v[28:29], v[138:139], v[114:115], v[28:29] op_sel_hi:[0,1,1]
	v_pk_fma_f32 v[128:129], v[138:139], v[122:123], v[28:29] op_sel:[1,0,0]
	ds_read_b128 v[28:31], v187 offset:22528
	ds_read_b128 v[32:35], v187 offset:23552
	ds_read_b128 v[20:23], v187 offset:24576
	ds_read_b128 v[88:91], v187 offset:25600
	ds_read_b128 v[96:99], v187 offset:26624
	ds_read_b128 v[100:103], v187 offset:27648
	ds_read_b128 v[108:111], v187 offset:28672
	ds_read_b128 v[112:115], v187 offset:29696
	ds_read_b128 v[116:119], v187 offset:30720
	ds_read_b128 v[120:123], v187 offset:31744
	s_waitcnt lgkmcnt(10)
	v_pk_fma_f32 v[24:25], v[140:141], v[24:25], v[84:85] op_sel_hi:[0,1,1]
	v_pk_fma_f32 v[84:85], v[136:137], v[130:131], v[128:129] op_sel_hi:[0,1,1]
	s_waitcnt lgkmcnt(9)
	v_pk_fma_f32 v[28:29], v[140:141], v[28:29], v[124:125] op_sel:[1,0,0]
	v_pk_fma_f32 v[30:31], v[140:141], v[30:31], v[126:127] op_sel:[1,0,0]
	s_waitcnt lgkmcnt(7)
	v_pk_fma_f32 v[20:21], v[134:135], v[20:21], v[28:29] op_sel_hi:[0,1,1]
	s_waitcnt lgkmcnt(5)
	v_pk_fma_f32 v[20:21], v[134:135], v[96:97], v[20:21] op_sel:[1,0,0]
	v_pk_fma_f32 v[22:23], v[134:135], v[22:23], v[30:31] op_sel_hi:[0,1,1]
	s_waitcnt lgkmcnt(3)
	v_pk_fma_f32 v[20:21], v[132:133], v[108:109], v[20:21] op_sel_hi:[0,1,1]
	s_waitcnt lgkmcnt(1)
	v_pk_fma_f32 v[20:21], v[132:133], v[116:117], v[20:21] op_sel:[1,0,0]
	s_waitcnt lgkmcnt(0)
; __device__ __forceinline__ void phase1(const Args& a, LAS unsigned char* L) {
;     ...
;         for (int q = 0; q < 8; ++q) gacc[q] = wave_sum(gacc[q]);
;         if (lane == 0) { *(f32x4*)(gates + (size_t)m * 8) = (f32x4){gacc[0], gacc[1], gacc[2], gacc[3]}; *(f32x4*)(gates + (size_t)m * 8 + 4) = (f32x4){gacc[4], gacc[5], gacc[6], gacc[7]}; }
	v_pk_fma_f32 v[22:23], v[134:135], v[98:99], v[22:23] op_sel:[1,0,0]
	v_pk_fma_f32 v[84:85], v[136:137], v[86:87], v[84:85] op_sel:[1,0,0]
	v_pk_fma_f32 v[22:23], v[132:133], v[110:111], v[22:23] op_sel_hi:[0,1,1]
	v_pk_fma_f32 v[22:23], v[132:133], v[118:119], v[22:23] op_sel:[1,0,0]
	v_pk_fma_f32 v[84:85], v[146:147], v[94:95], v[84:85] op_sel_hi:[0,1,1]
	v_pk_fma_f32 v[84:85], v[146:147], v[106:107], v[84:85] op_sel:[1,0,0]
	v_pk_fma_f32 v[26:27], v[140:141], v[26:27], v[84:85] op_sel_hi:[0,1,1]
	v_pk_fma_f32 v[24:25], v[140:141], v[32:33], v[24:25] op_sel:[1,0,0]
	v_pk_fma_f32 v[26:27], v[140:141], v[34:35], v[26:27] op_sel:[1,0,0]
	v_pk_fma_f32 v[24:25], v[134:135], v[88:89], v[24:25] op_sel_hi:[0,1,1]
	v_pk_fma_f32 v[26:27], v[134:135], v[90:91], v[26:27] op_sel_hi:[0,1,1]
	v_pk_fma_f32 v[24:25], v[134:135], v[100:101], v[24:25] op_sel:[1,0,0]
	v_pk_fma_f32 v[26:27], v[134:135], v[102:103], v[26:27] op_sel:[1,0,0]
	v_pk_fma_f32 v[24:25], v[132:133], v[112:113], v[24:25] op_sel_hi:[0,1,1]
	v_pk_fma_f32 v[26:27], v[132:133], v[114:115], v[26:27] op_sel_hi:[0,1,1]
	v_pk_fma_f32 v[24:25], v[132:133], v[120:121], v[24:25] op_sel:[1,0,0]
	v_pk_fma_f32 v[26:27], v[132:133], v[122:123], v[26:27] op_sel:[1,0,0]
	global_store_dwordx2 v[178:179], v[2:3], off offset:1024
	v_cvt_pk_bf16_f32 v2, v134, v135
	v_cvt_pk_bf16_f32 v3, v132, v133
	global_store_dwordx2 v[178:179], v[2:3], off offset:1536
	v_add_f32_dpp v20, v20, v20 row_shr:1 row_mask:0xf bank_mask:0xf bound_ctrl:1
	v_add_f32_dpp v21, v21, v21 row_shr:1 row_mask:0xf bank_mask:0xf bound_ctrl:1
	v_add_f32_dpp v22, v22, v22 row_shr:1 row_mask:0xf bank_mask:0xf bound_ctrl:1
	v_add_f32_dpp v23, v23, v23 row_shr:1 row_mask:0xf bank_mask:0xf bound_ctrl:1
	v_add_f32_dpp v24, v24, v24 row_shr:1 row_mask:0xf bank_mask:0xf bound_ctrl:1
	v_add_f32_dpp v25, v25, v25 row_shr:1 row_mask:0xf bank_mask:0xf bound_ctrl:1
	v_add_f32_dpp v26, v26, v26 row_shr:1 row_mask:0xf bank_mask:0xf bound_ctrl:1
	v_add_f32_dpp v27, v27, v27 row_shr:1 row_mask:0xf bank_mask:0xf bound_ctrl:1
	v_add_f32_dpp v20, v20, v20 row_shr:2 row_mask:0xf bank_mask:0xf bound_ctrl:1
	v_add_f32_dpp v21, v21, v21 row_shr:2 row_mask:0xf bank_mask:0xf bound_ctrl:1
	v_add_f32_dpp v22, v22, v22 row_shr:2 row_mask:0xf bank_mask:0xf bound_ctrl:1
	v_add_f32_dpp v23, v23, v23 row_shr:2 row_mask:0xf bank_mask:0xf bound_ctrl:1
	v_add_f32_dpp v24, v24, v24 row_shr:2 row_mask:0xf bank_mask:0xf bound_ctrl:1
	v_add_f32_dpp v25, v25, v25 row_shr:2 row_mask:0xf bank_mask:0xf bound_ctrl:1
	v_add_f32_dpp v26, v26, v26 row_shr:2 row_mask:0xf bank_mask:0xf bound_ctrl:1
	v_add_f32_dpp v27, v27, v27 row_shr:2 row_mask:0xf bank_mask:0xf bound_ctrl:1
	v_add_f32_dpp v20, v20, v20 row_shr:4 row_mask:0xf bank_mask:0xf bound_ctrl:1
	v_add_f32_dpp v21, v21, v21 row_shr:4 row_mask:0xf bank_mask:0xf bound_ctrl:1
	v_add_f32_dpp v22, v22, v22 row_shr:4 row_mask:0xf bank_mask:0xf bound_ctrl:1
	v_add_f32_dpp v23, v23, v23 row_shr:4 row_mask:0xf bank_mask:0xf bound_ctrl:1
	v_add_f32_dpp v24, v24, v24 row_shr:4 row_mask:0xf bank_mask:0xf bound_ctrl:1
	v_add_f32_dpp v25, v25, v25 row_shr:4 row_mask:0xf bank_mask:0xf bound_ctrl:1
	v_add_f32_dpp v26, v26, v26 row_shr:4 row_mask:0xf bank_mask:0xf bound_ctrl:1
	v_add_f32_dpp v27, v27, v27 row_shr:4 row_mask:0xf bank_mask:0xf bound_ctrl:1
	v_add_f32_dpp v20, v20, v20 row_shr:8 row_mask:0xf bank_mask:0xf bound_ctrl:1
	v_add_f32_dpp v21, v21, v21 row_shr:8 row_mask:0xf bank_mask:0xf bound_ctrl:1
	v_add_f32_dpp v22, v22, v22 row_shr:8 row_mask:0xf bank_mask:0xf bound_ctrl:1
	v_add_f32_dpp v23, v23, v23 row_shr:8 row_mask:0xf bank_mask:0xf bound_ctrl:1
	v_add_f32_dpp v24, v24, v24 row_shr:8 row_mask:0xf bank_mask:0xf bound_ctrl:1
	v_add_f32_dpp v25, v25, v25 row_shr:8 row_mask:0xf bank_mask:0xf bound_ctrl:1
	v_add_f32_dpp v26, v26, v26 row_shr:8 row_mask:0xf bank_mask:0xf bound_ctrl:1
	v_add_f32_dpp v27, v27, v27 row_shr:8 row_mask:0xf bank_mask:0xf bound_ctrl:1
	v_add_f32_dpp v20, v20, v20 row_bcast:15 row_mask:0xa bank_mask:0xf
	v_add_f32_dpp v21, v21, v21 row_bcast:15 row_mask:0xa bank_mask:0xf
	v_add_f32_dpp v22, v22, v22 row_bcast:15 row_mask:0xa bank_mask:0xf
	v_add_f32_dpp v23, v23, v23 row_bcast:15 row_mask:0xa bank_mask:0xf
	v_add_f32_dpp v24, v24, v24 row_bcast:15 row_mask:0xa bank_mask:0xf
	v_add_f32_dpp v25, v25, v25 row_bcast:15 row_mask:0xa bank_mask:0xf
	v_add_f32_dpp v26, v26, v26 row_bcast:15 row_mask:0xa bank_mask:0xf
	v_add_f32_dpp v27, v27, v27 row_bcast:15 row_mask:0xa bank_mask:0xf
	v_add_f32_dpp v20, v20, v20 row_bcast:31 row_mask:0xc bank_mask:0xf
	v_add_f32_dpp v21, v21, v21 row_bcast:31 row_mask:0xc bank_mask:0xf
	v_add_f32_dpp v22, v22, v22 row_bcast:31 row_mask:0xc bank_mask:0xf
	v_add_f32_dpp v23, v23, v23 row_bcast:31 row_mask:0xc bank_mask:0xf
	v_add_f32_dpp v24, v24, v24 row_bcast:31 row_mask:0xc bank_mask:0xf
	v_add_f32_dpp v25, v25, v25 row_bcast:31 row_mask:0xc bank_mask:0xf
	v_add_f32_dpp v26, v26, v26 row_bcast:31 row_mask:0xc bank_mask:0xf
	v_add_f32_dpp v27, v27, v27 row_bcast:31 row_mask:0xc bank_mask:0xf
	s_mov_b64 s[0:1], exec
	s_mov_b32 exec_lo, 0
	s_brev_b32 exec_hi, 1
	global_store_dwordx4 v1, v[20:23], s[6:7]
	global_store_dwordx4 v1, v[24:27], s[6:7] offset:16
	s_branch .LBB0_116
